# grid barrier: every workgroup polls the cross-XCD flag slots itself (no per-XCD release hop)
# baseline (speedup 1.0000x reference)
.LBB0_1114:
	s_or_b64 exec, exec, s[8:9]
	v_cvt_f32_u32_e32 v5, v3
	s_waitcnt vmcnt(0)
	v_readfirstlane_b32 s8, v4
	v_sub_u32_e32 v4, 0, v3
	v_rcp_iflag_f32_e32 v5, v5
	v_add_u32_e32 v6, s8, v0
	v_mul_f32_e32 v5, 0x4f7ffffe, v5
	v_cvt_u32_f32_e32 v5, v5
	v_mul_lo_u32 v0, v4, v5
	v_mul_hi_u32 v0, v5, v0
	v_add_u32_e32 v0, v5, v0
	v_mul_hi_u32 v0, v6, v0
	v_mul_lo_u32 v4, v0, v3
	v_sub_u32_e32 v4, v6, v4
	v_add_u32_e32 v5, 1, v0
	v_cmp_ge_u32_e32 vcc, v4, v3
	s_nop 1
	v_cndmask_b32_e32 v0, v0, v5, vcc
	v_sub_u32_e32 v5, v4, v3
	v_cndmask_b32_e32 v4, v4, v5, vcc
	v_add_u32_e32 v5, 1, v0
	v_cmp_ge_u32_e32 vcc, v4, v3
	v_add_u32_e32 v4, 1, v6
	s_nop 0
	v_cndmask_b32_e32 v0, v0, v5, vcc
	v_add_u32_e32 v7, 1, v0
	v_mul_lo_u32 v5, v3, v0
	v_add_u32_e32 v3, v5, v3
	v_cmp_ne_u32_e32 vcc, v4, v3
	s_and_saveexec_b64 s[8:9], vcc
	s_xor_b64 s[8:9], exec, s[8:9]
	s_cbranch_execz .LBB0_1128
	v_readfirstlane_b32 s28, v2
	v_readfirstlane_b32 s22, v0
	s_add_i32 s22, s22, 1
	v_readlane_b32 s10, v253, 30
	v_readlane_b32 s11, v253, 31
	s_add_u32 s10, s10, 0x8000
	s_addc_u32 s11, s11, 0
	s_waitcnt lgkmcnt(0)
	s_nop 3
	buffer_inv sc1
	s_mov_b64 s[26:27], exec
	s_mov_b64 exec, 0xff
	v_mbcnt_lo_u32_b32 v6, -1, 0
	v_lshlrev_b32_e32 v6, 2, v6

.Lxn_all:
	s_mov_b64 exec, s[26:27]
	s_mov_b64 s[10:11], exec
